# P7 SwiGLU epilogue segments 2-8: scalar f32 mul/add merged into v_pk_mul_f32/v_pk_add_f32 (same f32 math, same association), math grouped by op type
# speedup vs baseline: 1.0089x; 1.0089x over previous
.LBB0_959:
	s_mov_b32 s98, 0xbfb8aa3b
	s_mov_b32 s99, 0xbfb8aa3b
	v_mul_f32_e32 v153, 0xbfb8aa3b, v124
	v_exp_f32_e32 v153, v153
	v_mul_f32_e32 v154, 0xbfb8aa3b, v125
	v_exp_f32_e32 v156, v154
	v_lshl_add_u32 v146, s18, 8, v148
	v_ashrrev_i32_e32 v147, 31, v146
	v_lshlrev_b64 v[154:155], 6, v[146:147]
	v_add_f32_e32 v147, 1.0, v153
	v_rcp_f32_e32 v147, v147
	v_add_f32_e32 v153, 1.0, v156
	v_rcp_f32_e32 v153, v153
	s_lshl_b32 s11, s19, 2
	v_mul_f32_e32 v124, v124, v147
	v_mul_f32_e32 v124, v124, v116
	v_mul_f32_e32 v116, v125, v153
	v_mul_f32_e32 v125, 0xbfb8aa3b, v126
	v_exp_f32_e32 v125, v125
	v_mul_f32_e32 v147, 0xbfb8aa3b, v127
	v_exp_f32_e32 v147, v147
	v_mul_f32_e32 v153, v116, v117
	v_add_f32_e32 v116, 1.0, v125
	v_rcp_f32_e32 v116, v116
	v_add_f32_e32 v117, 1.0, v147
	v_mul_f32_e32 v125, 0xbfb8aa3b, v120
	v_rcp_f32_e32 v117, v117
	v_exp_f32_e32 v125, v125
	v_mul_f32_e32 v116, v126, v116
	v_mul_f32_e32 v118, v116, v118
	v_mul_f32_e32 v116, v127, v117
	v_add_f32_e32 v117, 1.0, v125
	v_rcp_f32_e32 v117, v117
	v_mul_f32_e32 v125, 0xbfb8aa3b, v121
	v_mul_f32_e32 v119, v116, v119
	v_exp_f32_e32 v125, v125
	v_mul_f32_e32 v116, v120, v117
	v_mul_f32_e32 v120, v116, v112
	v_mul_f32_e32 v116, 0xbfb8aa3b, v122
	v_exp_f32_e32 v116, v116
	v_mul_f32_e32 v117, 0xbfb8aa3b, v123
	v_exp_f32_e32 v117, v117
	v_add_f32_e32 v112, 1.0, v125
	v_rcp_f32_e32 v112, v112
	v_add_f32_e32 v116, 1.0, v116
	v_rcp_f32_e32 v116, v116
	v_add_f32_e32 v117, 1.0, v117
	s_or_b32 s11, s11, s44
	v_rcp_f32_e32 v117, v117
	s_mul_hi_i32 s13, s11, 0x500000
	s_mul_i32 s11, s11, 0x500000
	s_add_u32 s18, s42, s11
	v_mul_f32_e32 v112, v121, v112
	s_addc_u32 s19, s43, s13
	v_mul_f32_e32 v121, v112, v113
	v_mul_f32_e32 v112, v122, v116
	v_lshl_add_u64 v[154:155], s[18:19], 0, v[154:155]
	v_mul_f32_e32 v122, v112, v114
	v_mul_f32_e32 v112, v123, v117
	v_mul_f32_e32 v115, v112, v115
	v_lshl_add_u64 v[116:117], v[154:155], 0, v[136:137]
	v_cvt_pk_bf16_f32 v112, v124, v153
	v_cvt_pk_bf16_f32 v113, v118, v119
	v_cvt_pk_bf16_f32 v114, v120, v121
	v_cvt_pk_bf16_f32 v115, v122, v115
	global_store_dwordx4 v[116:117], v[112:115], off
	s_nop 0
	s_andn2_b64 vcc, exec, s[2:3]
	s_mov_b64 s[2:3], -1
	v_or_b32_e32 v112, 16, v146
	v_ashrrev_i32_e32 v113, 31, v112
	v_lshlrev_b64 v[112:113], 6, v[112:113]
	v_lshl_add_u64 v[112:113], s[18:19], 0, v[112:113]
	v_pk_mul_f32 v[114:115], v[108:109], s[98:99]
	v_pk_mul_f32 v[116:117], v[110:111], s[98:99]
	v_pk_mul_f32 v[118:119], v[104:105], s[98:99]
	v_pk_mul_f32 v[120:121], v[106:107], s[98:99]
	v_exp_f32_e32 v114, v114
	v_exp_f32_e32 v115, v115
	v_exp_f32_e32 v116, v116
	v_exp_f32_e32 v117, v117
	v_exp_f32_e32 v118, v118
	v_exp_f32_e32 v119, v119
	v_exp_f32_e32 v120, v120
	v_exp_f32_e32 v121, v121
	v_pk_add_f32 v[114:115], v[114:115], 1.0 op_sel_hi:[1,0]
	v_pk_add_f32 v[116:117], v[116:117], 1.0 op_sel_hi:[1,0]
	v_pk_add_f32 v[118:119], v[118:119], 1.0 op_sel_hi:[1,0]
	v_pk_add_f32 v[120:121], v[120:121], 1.0 op_sel_hi:[1,0]
	v_rcp_f32_e32 v114, v114
	v_rcp_f32_e32 v115, v115
	v_rcp_f32_e32 v116, v116
	v_rcp_f32_e32 v117, v117
	v_rcp_f32_e32 v118, v118
	v_rcp_f32_e32 v119, v119
	v_rcp_f32_e32 v120, v120
	v_rcp_f32_e32 v121, v121
	v_pk_mul_f32 v[108:109], v[108:109], v[114:115]
	v_pk_mul_f32 v[110:111], v[110:111], v[116:117]
	v_pk_mul_f32 v[104:105], v[104:105], v[118:119]
	v_pk_mul_f32 v[106:107], v[106:107], v[120:121]
	v_pk_mul_f32 v[108:109], v[108:109], v[100:101]
	v_pk_mul_f32 v[110:111], v[110:111], v[102:103]
	v_pk_mul_f32 v[104:105], v[104:105], v[96:97]
	v_pk_mul_f32 v[106:107], v[106:107], v[98:99]
	v_lshl_add_u64 v[100:101], v[112:113], 0, v[136:137]
	v_cvt_pk_bf16_f32 v96, v108, v109
	v_cvt_pk_bf16_f32 v97, v110, v111
	v_cvt_pk_bf16_f32 v98, v104, v105
	v_cvt_pk_bf16_f32 v99, v106, v107
	global_store_dwordx4 v[100:101], v[96:99], off
	s_nop 0
	s_nop 1
	v_or_b32_e32 v96, 32, v146
	v_ashrrev_i32_e32 v97, 31, v96
	v_lshlrev_b64 v[96:97], 6, v[96:97]
	v_lshl_add_u64 v[96:97], s[18:19], 0, v[96:97]
	v_pk_mul_f32 v[98:99], v[92:93], s[98:99]
	v_pk_mul_f32 v[100:101], v[94:95], s[98:99]
	v_pk_mul_f32 v[102:103], v[88:89], s[98:99]
	v_pk_mul_f32 v[104:105], v[90:91], s[98:99]
	v_exp_f32_e32 v98, v98
	v_exp_f32_e32 v99, v99
	v_exp_f32_e32 v100, v100
	v_exp_f32_e32 v101, v101
	v_exp_f32_e32 v102, v102
	v_exp_f32_e32 v103, v103
	v_exp_f32_e32 v104, v104
	v_exp_f32_e32 v105, v105
	v_pk_add_f32 v[98:99], v[98:99], 1.0 op_sel_hi:[1,0]
	v_pk_add_f32 v[100:101], v[100:101], 1.0 op_sel_hi:[1,0]
	v_pk_add_f32 v[102:103], v[102:103], 1.0 op_sel_hi:[1,0]
	v_pk_add_f32 v[104:105], v[104:105], 1.0 op_sel_hi:[1,0]
	v_rcp_f32_e32 v98, v98
	v_rcp_f32_e32 v99, v99
	v_rcp_f32_e32 v100, v100
	v_rcp_f32_e32 v101, v101
	v_rcp_f32_e32 v102, v102
	v_rcp_f32_e32 v103, v103
	v_rcp_f32_e32 v104, v104
	v_rcp_f32_e32 v105, v105
	v_pk_mul_f32 v[92:93], v[92:93], v[98:99]
	v_pk_mul_f32 v[94:95], v[94:95], v[100:101]
	v_pk_mul_f32 v[88:89], v[88:89], v[102:103]
	v_pk_mul_f32 v[90:91], v[90:91], v[104:105]
	v_pk_mul_f32 v[92:93], v[92:93], v[84:85]
	v_pk_mul_f32 v[94:95], v[94:95], v[86:87]
	v_pk_mul_f32 v[88:89], v[88:89], v[80:81]
	v_pk_mul_f32 v[90:91], v[90:91], v[82:83]
	v_lshl_add_u64 v[84:85], v[96:97], 0, v[136:137]
	v_cvt_pk_bf16_f32 v80, v92, v93
	v_cvt_pk_bf16_f32 v81, v94, v95
	v_cvt_pk_bf16_f32 v82, v88, v89
	v_cvt_pk_bf16_f32 v83, v90, v91
	global_store_dwordx4 v[84:85], v[80:83], off
	s_nop 0
	s_nop 1
	v_or_b32_e32 v80, 48, v146
	v_ashrrev_i32_e32 v81, 31, v80
	v_lshlrev_b64 v[80:81], 6, v[80:81]
	v_lshl_add_u64 v[80:81], s[18:19], 0, v[80:81]
	v_pk_mul_f32 v[82:83], v[76:77], s[98:99]
	v_pk_mul_f32 v[84:85], v[78:79], s[98:99]
	v_pk_mul_f32 v[86:87], v[72:73], s[98:99]
	v_pk_mul_f32 v[88:89], v[74:75], s[98:99]
	v_exp_f32_e32 v82, v82
	v_exp_f32_e32 v83, v83
	v_exp_f32_e32 v84, v84
	v_exp_f32_e32 v85, v85
	v_exp_f32_e32 v86, v86
	v_exp_f32_e32 v87, v87
	v_exp_f32_e32 v88, v88
	v_exp_f32_e32 v89, v89
	v_pk_add_f32 v[82:83], v[82:83], 1.0 op_sel_hi:[1,0]
	v_pk_add_f32 v[84:85], v[84:85], 1.0 op_sel_hi:[1,0]
	v_pk_add_f32 v[86:87], v[86:87], 1.0 op_sel_hi:[1,0]
	v_pk_add_f32 v[88:89], v[88:89], 1.0 op_sel_hi:[1,0]
	v_rcp_f32_e32 v82, v82
	v_rcp_f32_e32 v83, v83
	v_rcp_f32_e32 v84, v84
	v_rcp_f32_e32 v85, v85
	v_rcp_f32_e32 v86, v86
	v_rcp_f32_e32 v87, v87
	v_rcp_f32_e32 v88, v88
	v_rcp_f32_e32 v89, v89
	v_pk_mul_f32 v[76:77], v[76:77], v[82:83]
	v_pk_mul_f32 v[78:79], v[78:79], v[84:85]
	v_pk_mul_f32 v[72:73], v[72:73], v[86:87]
	v_pk_mul_f32 v[74:75], v[74:75], v[88:89]
	v_pk_mul_f32 v[76:77], v[76:77], v[68:69]
	v_pk_mul_f32 v[78:79], v[78:79], v[70:71]
	v_pk_mul_f32 v[72:73], v[72:73], v[64:65]
	v_pk_mul_f32 v[74:75], v[74:75], v[66:67]
	v_lshl_add_u64 v[68:69], v[80:81], 0, v[136:137]
	v_cvt_pk_bf16_f32 v64, v76, v77
	v_cvt_pk_bf16_f32 v65, v78, v79
	v_cvt_pk_bf16_f32 v66, v72, v73
	v_cvt_pk_bf16_f32 v67, v74, v75
	global_store_dwordx4 v[68:69], v[64:67], off
	s_nop 0
	s_nop 1
	v_add_u32_e32 v64, 0x80, v146
	v_ashrrev_i32_e32 v65, 31, v64
	v_lshlrev_b64 v[64:65], 6, v[64:65]
	v_lshl_add_u64 v[64:65], s[18:19], 0, v[64:65]
	v_pk_mul_f32 v[66:67], v[60:61], s[98:99]
	v_pk_mul_f32 v[68:69], v[62:63], s[98:99]
	v_pk_mul_f32 v[70:71], v[56:57], s[98:99]
	v_pk_mul_f32 v[72:73], v[58:59], s[98:99]
	v_exp_f32_e32 v66, v66
	v_exp_f32_e32 v67, v67
	v_exp_f32_e32 v68, v68
	v_exp_f32_e32 v69, v69
	v_exp_f32_e32 v70, v70
	v_exp_f32_e32 v71, v71
	v_exp_f32_e32 v72, v72
	v_exp_f32_e32 v73, v73
	v_pk_add_f32 v[66:67], v[66:67], 1.0 op_sel_hi:[1,0]
	v_pk_add_f32 v[68:69], v[68:69], 1.0 op_sel_hi:[1,0]
	v_pk_add_f32 v[70:71], v[70:71], 1.0 op_sel_hi:[1,0]
	v_pk_add_f32 v[72:73], v[72:73], 1.0 op_sel_hi:[1,0]
	v_rcp_f32_e32 v66, v66
	v_rcp_f32_e32 v67, v67
	v_rcp_f32_e32 v68, v68
	v_rcp_f32_e32 v69, v69
	v_rcp_f32_e32 v70, v70
	v_rcp_f32_e32 v71, v71
	v_rcp_f32_e32 v72, v72
	v_rcp_f32_e32 v73, v73
	v_pk_mul_f32 v[60:61], v[60:61], v[66:67]
	v_pk_mul_f32 v[62:63], v[62:63], v[68:69]
	v_pk_mul_f32 v[56:57], v[56:57], v[70:71]
	v_pk_mul_f32 v[58:59], v[58:59], v[72:73]
	v_pk_mul_f32 v[60:61], v[60:61], v[52:53]
	v_pk_mul_f32 v[62:63], v[62:63], v[54:55]
	v_pk_mul_f32 v[56:57], v[56:57], v[48:49]
	v_pk_mul_f32 v[58:59], v[58:59], v[50:51]
	v_lshl_add_u64 v[52:53], v[64:65], 0, v[136:137]
	v_cvt_pk_bf16_f32 v48, v60, v61
	v_cvt_pk_bf16_f32 v49, v62, v63
	v_cvt_pk_bf16_f32 v50, v56, v57
	v_cvt_pk_bf16_f32 v51, v58, v59
	global_store_dwordx4 v[52:53], v[48:51], off
	s_nop 0
	s_nop 1
	v_add_u32_e32 v48, 0x90, v146
	v_ashrrev_i32_e32 v49, 31, v48
	v_lshlrev_b64 v[48:49], 6, v[48:49]
	v_lshl_add_u64 v[48:49], s[18:19], 0, v[48:49]
	v_pk_mul_f32 v[50:51], v[44:45], s[98:99]
	v_pk_mul_f32 v[52:53], v[46:47], s[98:99]
	v_pk_mul_f32 v[54:55], v[40:41], s[98:99]
	v_pk_mul_f32 v[56:57], v[42:43], s[98:99]
	v_exp_f32_e32 v50, v50
	v_exp_f32_e32 v51, v51
	v_exp_f32_e32 v52, v52
	v_exp_f32_e32 v53, v53
	v_exp_f32_e32 v54, v54
	v_exp_f32_e32 v55, v55
	v_exp_f32_e32 v56, v56
	v_exp_f32_e32 v57, v57
	v_pk_add_f32 v[50:51], v[50:51], 1.0 op_sel_hi:[1,0]
	v_pk_add_f32 v[52:53], v[52:53], 1.0 op_sel_hi:[1,0]
	v_pk_add_f32 v[54:55], v[54:55], 1.0 op_sel_hi:[1,0]
	v_pk_add_f32 v[56:57], v[56:57], 1.0 op_sel_hi:[1,0]
	v_rcp_f32_e32 v50, v50
	v_rcp_f32_e32 v51, v51
	v_rcp_f32_e32 v52, v52
	v_rcp_f32_e32 v53, v53
	v_rcp_f32_e32 v54, v54
	v_rcp_f32_e32 v55, v55
	v_rcp_f32_e32 v56, v56
	v_rcp_f32_e32 v57, v57
	v_pk_mul_f32 v[44:45], v[44:45], v[50:51]
	v_pk_mul_f32 v[46:47], v[46:47], v[52:53]
	v_pk_mul_f32 v[40:41], v[40:41], v[54:55]
	v_pk_mul_f32 v[42:43], v[42:43], v[56:57]
	v_pk_mul_f32 v[44:45], v[44:45], v[36:37]
	v_pk_mul_f32 v[46:47], v[46:47], v[38:39]
	v_pk_mul_f32 v[40:41], v[40:41], v[32:33]
	v_pk_mul_f32 v[42:43], v[42:43], v[34:35]
	v_lshl_add_u64 v[36:37], v[48:49], 0, v[136:137]
	v_cvt_pk_bf16_f32 v32, v44, v45
	v_cvt_pk_bf16_f32 v33, v46, v47
	v_cvt_pk_bf16_f32 v34, v40, v41
	v_cvt_pk_bf16_f32 v35, v42, v43
	global_store_dwordx4 v[36:37], v[32:35], off
	s_nop 0
	s_nop 1
	v_add_u32_e32 v32, 0xa0, v146
	v_ashrrev_i32_e32 v33, 31, v32
	v_lshlrev_b64 v[32:33], 6, v[32:33]
	v_lshl_add_u64 v[32:33], s[18:19], 0, v[32:33]
	v_pk_mul_f32 v[34:35], v[28:29], s[98:99]
	v_pk_mul_f32 v[36:37], v[30:31], s[98:99]
	v_pk_mul_f32 v[38:39], v[24:25], s[98:99]
	v_pk_mul_f32 v[40:41], v[26:27], s[98:99]
	v_exp_f32_e32 v34, v34
	v_exp_f32_e32 v35, v35
	v_exp_f32_e32 v36, v36
	v_exp_f32_e32 v37, v37
	v_exp_f32_e32 v38, v38
	v_exp_f32_e32 v39, v39
	v_exp_f32_e32 v40, v40
	v_exp_f32_e32 v41, v41
	v_pk_add_f32 v[34:35], v[34:35], 1.0 op_sel_hi:[1,0]
	v_pk_add_f32 v[36:37], v[36:37], 1.0 op_sel_hi:[1,0]
	v_pk_add_f32 v[38:39], v[38:39], 1.0 op_sel_hi:[1,0]
	v_pk_add_f32 v[40:41], v[40:41], 1.0 op_sel_hi:[1,0]
	v_rcp_f32_e32 v34, v34
	v_rcp_f32_e32 v35, v35
	v_rcp_f32_e32 v36, v36
	v_rcp_f32_e32 v37, v37
	v_rcp_f32_e32 v38, v38
	v_rcp_f32_e32 v39, v39
	v_rcp_f32_e32 v40, v40
	v_rcp_f32_e32 v41, v41
	v_pk_mul_f32 v[28:29], v[28:29], v[34:35]
	v_pk_mul_f32 v[30:31], v[30:31], v[36:37]
	v_pk_mul_f32 v[24:25], v[24:25], v[38:39]
	v_pk_mul_f32 v[26:27], v[26:27], v[40:41]
	v_pk_mul_f32 v[28:29], v[28:29], v[20:21]
	v_pk_mul_f32 v[30:31], v[30:31], v[22:23]
	v_pk_mul_f32 v[24:25], v[24:25], v[16:17]
	v_pk_mul_f32 v[26:27], v[26:27], v[18:19]
	v_lshl_add_u64 v[20:21], v[32:33], 0, v[136:137]
	v_cvt_pk_bf16_f32 v16, v28, v29
	v_cvt_pk_bf16_f32 v17, v30, v31
	v_cvt_pk_bf16_f32 v18, v24, v25
	v_cvt_pk_bf16_f32 v19, v26, v27
	global_store_dwordx4 v[20:21], v[16:19], off
	s_nop 0
	s_nop 1
	v_add_u32_e32 v16, 0xb0, v146
	v_ashrrev_i32_e32 v17, 31, v16
	v_lshlrev_b64 v[16:17], 6, v[16:17]
	v_lshl_add_u64 v[16:17], s[18:19], 0, v[16:17]
	v_pk_mul_f32 v[18:19], v[12:13], s[98:99]
	v_pk_mul_f32 v[20:21], v[14:15], s[98:99]
	v_pk_mul_f32 v[22:23], v[8:9], s[98:99]
	v_pk_mul_f32 v[24:25], v[10:11], s[98:99]
	v_exp_f32_e32 v18, v18
	v_exp_f32_e32 v19, v19
	v_exp_f32_e32 v20, v20
	v_exp_f32_e32 v21, v21
	v_exp_f32_e32 v22, v22
	v_exp_f32_e32 v23, v23
	v_exp_f32_e32 v24, v24
	v_exp_f32_e32 v25, v25
	v_pk_add_f32 v[18:19], v[18:19], 1.0 op_sel_hi:[1,0]
	v_pk_add_f32 v[20:21], v[20:21], 1.0 op_sel_hi:[1,0]
	v_pk_add_f32 v[22:23], v[22:23], 1.0 op_sel_hi:[1,0]
	v_pk_add_f32 v[24:25], v[24:25], 1.0 op_sel_hi:[1,0]
	v_rcp_f32_e32 v18, v18
	v_rcp_f32_e32 v19, v19
	v_rcp_f32_e32 v20, v20
	v_rcp_f32_e32 v21, v21
	v_rcp_f32_e32 v22, v22
	v_rcp_f32_e32 v23, v23
	v_rcp_f32_e32 v24, v24
	v_rcp_f32_e32 v25, v25
	v_pk_mul_f32 v[12:13], v[12:13], v[18:19]
	v_pk_mul_f32 v[14:15], v[14:15], v[20:21]
	v_pk_mul_f32 v[8:9], v[8:9], v[22:23]
	v_pk_mul_f32 v[10:11], v[10:11], v[24:25]
	v_pk_mul_f32 v[12:13], v[12:13], v[4:5]
	v_pk_mul_f32 v[14:15], v[14:15], v[6:7]
	v_pk_mul_f32 v[8:9], v[8:9], v[0:1]
	v_pk_mul_f32 v[10:11], v[10:11], v[2:3]
	v_lshl_add_u64 v[4:5], v[16:17], 0, v[136:137]
	v_cvt_pk_bf16_f32 v0, v12, v13
	v_cvt_pk_bf16_f32 v1, v14, v15
	v_cvt_pk_bf16_f32 v2, v8, v9
	v_cvt_pk_bf16_f32 v3, v10, v11
	global_store_dwordx4 v[4:5], v[0:3], off
	s_cbranch_vccnz .LBB0_952
	s_andn2_b64 vcc, exec, s[4:5]
	s_cbranch_vccnz .LBB0_951
	s_barrier
	s_branch .LBB0_951
